# MoE down-projection epilogue: row exchange between lanes 16 apart with v_permlane16_swap instead of select + LDS permute + merge
# speedup vs baseline: 1.0024x; 1.0024x over previous
.LBB0_1064:
	v_pk_add_f32 v[2:3], v[32:33], v[172:173]
	v_pk_add_f32 v[6:7], v[36:37], v[168:169]
	v_mul_f32_e32 v2, 0x42000000, v2
	v_mul_f32_e32 v3, 0x42000000, v3
	v_mov_b32_e32 v8, v213
	v_cvt_pk_fp8_f32 v8, v2, v3
	v_mul_f32_e32 v2, 0x42000000, v6
	v_mul_f32_e32 v3, 0x42000000, v7
	v_mov_b32_e32 v9, v213
	v_cvt_pk_fp8_f32 v9, v2, v3
	v_pk_add_f32 v[2:3], v[32:33], v[164:165]
	v_pk_add_f32 v[0:1], v[34:35], v[174:175]
	v_pk_add_f32 v[6:7], v[36:37], v[160:161]
	v_mul_f32_e32 v2, 0x42000000, v2
	v_mul_f32_e32 v3, 0x42000000, v3
	v_mov_b32_e32 v10, v213
	v_pk_add_f32 v[4:5], v[38:39], v[170:171]
	v_mul_f32_e32 v0, 0x42000000, v0
	v_mul_f32_e32 v1, 0x42000000, v1
	v_cvt_pk_fp8_f32 v10, v2, v3
	v_mul_f32_e32 v2, 0x42000000, v6
	v_mul_f32_e32 v3, 0x42000000, v7
	v_mov_b32_e32 v6, v213
	v_cvt_pk_fp8_f32 v8, v0, v1 op_sel:[0,0,1]
	v_mul_f32_e32 v0, 0x42000000, v4
	v_mul_f32_e32 v1, 0x42000000, v5
	v_cvt_pk_fp8_f32 v6, v2, v3
	v_cvt_pk_fp8_f32 v9, v0, v1 op_sel:[0,0,1]
	v_pk_add_f32 v[0:1], v[34:35], v[166:167]
	v_pk_add_f32 v[4:5], v[38:39], v[162:163]
	v_mul_f32_e32 v0, 0x42000000, v0
	v_mul_f32_e32 v1, 0x42000000, v1
	v_cvt_pk_fp8_f32 v10, v0, v1 op_sel:[0,0,1]
	v_mul_f32_e32 v0, 0x42000000, v4
	v_mul_f32_e32 v1, 0x42000000, v5
	v_cvt_pk_fp8_f32 v6, v0, v1 op_sel:[0,0,1]
	v_pk_add_f32 v[14:15], v[36:37], v[152:153]
	v_mov_b32_e32 v16, v213
	s_waitcnt lgkmcnt(0)
	v_mov_b32_e32 v4, v10
	v_pk_add_f32 v[10:11], v[32:33], v[156:157]
	v_mov_b32_e32 v17, v213
	v_mov_b32_e32 v5, v6
	v_mov_b32_e32 v3, v9
	v_mov_b32_e32 v2, v8
	s_nop 1
	v_permlane16_swap_b32_e32 v2, v4
	v_permlane16_swap_b32_e32 v3, v5
	v_pk_add_f32 v[8:9], v[34:35], v[158:159]
	v_mul_f32_e32 v7, 0x42000000, v10
	v_mul_f32_e32 v10, 0x42000000, v11
	v_cvt_pk_fp8_f32 v16, v7, v10
	v_mul_f32_e32 v7, 0x42000000, v8
	v_mul_f32_e32 v8, 0x42000000, v9
	v_mul_f32_e32 v9, 0x42000000, v14
	v_mul_f32_e32 v10, 0x42000000, v15
	v_cvt_pk_fp8_f32 v17, v9, v10
	v_pk_add_f32 v[12:13], v[38:39], v[154:155]
	v_cvt_pk_fp8_f32 v16, v7, v8 op_sel:[0,0,1]
	v_mul_f32_e32 v7, 0x42000000, v12
	v_mul_f32_e32 v8, 0x42000000, v13
	v_pk_add_f32 v[10:11], v[32:33], v[148:149]
	v_cvt_pk_fp8_f32 v17, v7, v8 op_sel:[0,0,1]
	v_pk_add_f32 v[8:9], v[34:35], v[150:151]
	v_pk_add_f32 v[14:15], v[36:37], v[144:145]
	v_mul_f32_e32 v7, 0x42000000, v10
	v_mul_f32_e32 v10, 0x42000000, v11
	v_mov_b32_e32 v11, v213
	v_cvt_pk_fp8_f32 v11, v7, v10
	v_mul_f32_e32 v7, 0x42000000, v8
	v_mul_f32_e32 v8, 0x42000000, v9
	v_mul_f32_e32 v9, 0x42000000, v14
	v_mul_f32_e32 v10, 0x42000000, v15
	v_mov_b32_e32 v14, v213
	v_cvt_pk_fp8_f32 v14, v9, v10
	v_pk_add_f32 v[12:13], v[38:39], v[146:147]
	v_cvt_pk_fp8_f32 v11, v7, v8 op_sel:[0,0,1]
	v_mul_f32_e32 v7, 0x42000000, v12
	v_mul_f32_e32 v8, 0x42000000, v13
	v_cvt_pk_fp8_f32 v14, v7, v8 op_sel:[0,0,1]
	v_add_u32_e32 v18, s55, v198
	v_add_u32_e32 v6, v18, v201
	v_ashrrev_i32_e32 v7, 31, v6
	v_or_b32_e32 v0, s96, v203
	v_lshlrev_b64 v[6:7], 10, v[6:7]
	v_ashrrev_i32_e32 v1, 31, v0
	v_lshl_add_u64 v[6:7], s[16:17], 0, v[6:7]
	v_lshl_add_u64 v[6:7], v[6:7], 0, v[0:1]
	v_pk_add_f32 v[12:13], v[40:41], v[140:141]
	global_store_dwordx4 v[6:7], v[2:5], off
	v_mov_b32_e32 v19, v213
	v_mov_b32_e32 v20, v213
	s_waitcnt lgkmcnt(0)
	v_mov_b32_e32 v5, v14
	v_mov_b32_e32 v4, v11
	v_mov_b32_e32 v3, v17
	v_mov_b32_e32 v2, v16
	s_nop 1
	v_permlane16_swap_b32_e32 v2, v4
	v_permlane16_swap_b32_e32 v3, v5
	v_pk_add_f32 v[10:11], v[42:43], v[142:143]
	v_pk_add_f32 v[16:17], v[44:45], v[136:137]
	v_mul_f32_e32 v9, 0x42000000, v12
	v_mul_f32_e32 v12, 0x42000000, v13
	v_cvt_pk_fp8_f32 v19, v9, v12
	v_mul_f32_e32 v9, 0x42000000, v10
	v_mul_f32_e32 v10, 0x42000000, v11
	v_mul_f32_e32 v11, 0x42000000, v16
	v_mul_f32_e32 v12, 0x42000000, v17
	v_cvt_pk_fp8_f32 v20, v11, v12
	v_pk_add_f32 v[14:15], v[46:47], v[138:139]
	v_cvt_pk_fp8_f32 v19, v9, v10 op_sel:[0,0,1]
	v_mul_f32_e32 v9, 0x42000000, v14
	v_mul_f32_e32 v10, 0x42000000, v15
	v_pk_add_f32 v[12:13], v[40:41], v[132:133]
	v_cvt_pk_fp8_f32 v20, v9, v10 op_sel:[0,0,1]
	v_pk_add_f32 v[10:11], v[42:43], v[134:135]
	v_pk_add_f32 v[16:17], v[44:45], v[128:129]
	v_mul_f32_e32 v9, 0x42000000, v12
	v_mul_f32_e32 v12, 0x42000000, v13
	v_mov_b32_e32 v13, v213
	v_cvt_pk_fp8_f32 v13, v9, v12
	v_mul_f32_e32 v9, 0x42000000, v10
	v_mul_f32_e32 v10, 0x42000000, v11
	v_mul_f32_e32 v11, 0x42000000, v16
	v_mul_f32_e32 v12, 0x42000000, v17
	v_mov_b32_e32 v16, v213
	v_cvt_pk_fp8_f32 v16, v11, v12
	v_pk_add_f32 v[14:15], v[46:47], v[130:131]
	v_cvt_pk_fp8_f32 v13, v9, v10 op_sel:[0,0,1]
	v_mul_f32_e32 v9, 0x42000000, v14
	v_mul_f32_e32 v10, 0x42000000, v15
	v_cvt_pk_fp8_f32 v16, v9, v10 op_sel:[0,0,1]
	v_add_u32_e32 v8, v18, v202
	v_ashrrev_i32_e32 v9, 31, v8
	v_lshlrev_b64 v[8:9], 10, v[8:9]
	v_lshl_add_u64 v[8:9], s[16:17], 0, v[8:9]
	v_lshl_add_u64 v[8:9], v[8:9], 0, v[0:1]
	global_store_dwordx4 v[8:9], v[2:5], off
	v_mov_b32_e32 v22, v213
	v_pk_add_f32 v[14:15], v[46:47], v[114:115]
	s_waitcnt lgkmcnt(0)
	v_mov_b32_e32 v4, v13
	v_pk_add_f32 v[12:13], v[40:41], v[116:117]
	v_mov_b32_e32 v5, v16
	v_mov_b32_e32 v3, v20
	v_pk_add_f32 v[10:11], v[42:43], v[118:119]
	v_pk_add_f32 v[16:17], v[44:45], v[112:113]
	v_mul_f32_e32 v2, 0x42000000, v12
	v_mul_f32_e32 v12, 0x42000000, v13
	v_mov_b32_e32 v20, v213
	v_cvt_pk_fp8_f32 v20, v2, v12
	v_mul_f32_e32 v2, 0x42000000, v10
	v_mul_f32_e32 v10, 0x42000000, v11
	v_mul_f32_e32 v11, 0x42000000, v16
	v_mul_f32_e32 v12, 0x42000000, v17
	v_cvt_pk_fp8_f32 v22, v11, v12
	v_cvt_pk_fp8_f32 v20, v2, v10 op_sel:[0,0,1]
	v_mul_f32_e32 v2, 0x42000000, v14
	v_mul_f32_e32 v10, 0x42000000, v15
	v_pk_add_f32 v[12:13], v[40:41], v[100:101]
	v_pk_add_f32 v[16:17], v[44:45], v[96:97]
	v_cvt_pk_fp8_f32 v22, v2, v10 op_sel:[0,0,1]
	v_mul_f32_e32 v2, 0x42000000, v12
	v_mul_f32_e32 v12, 0x42000000, v13
	v_mul_f32_e32 v13, 0x42000000, v16
	v_mul_f32_e32 v16, 0x42000000, v17
	v_mov_b32_e32 v17, v213
	v_cvt_pk_fp8_f32 v17, v13, v16
	v_pk_add_f32 v[14:15], v[46:47], v[98:99]
	v_mov_b32_e32 v23, v213
	v_cvt_pk_fp8_f32 v23, v2, v12
	v_mul_f32_e32 v2, 0x42000000, v14
	v_mul_f32_e32 v12, 0x42000000, v15
	v_cvt_pk_fp8_f32 v17, v2, v12 op_sel:[0,0,1]
	v_pk_add_f32 v[10:11], v[42:43], v[102:103]
	v_pk_add_f32 v[12:13], v[36:37], v[120:121]
	v_mul_f32_e32 v2, 0x42000000, v10
	v_mul_f32_e32 v10, 0x42000000, v11
	v_cvt_pk_fp8_f32 v23, v2, v10 op_sel:[0,0,1]
	v_mov_b32_e32 v2, v19
	s_nop 1
	v_permlane16_swap_b32_e32 v2, v4
	v_permlane16_swap_b32_e32 v3, v5
	global_store_dwordx4 v[6:7], v[2:5], off offset:128
	v_pk_add_f32 v[6:7], v[32:33], v[124:125]
	v_mov_b32_e32 v16, v213
	v_mul_f32_e32 v4, 0x42000000, v6
	v_mul_f32_e32 v6, 0x42000000, v7
	s_waitcnt lgkmcnt(0)
	v_mov_b32_e32 v5, v17
	v_cvt_pk_fp8_f32 v16, v4, v6
	v_mul_f32_e32 v4, 0x42000000, v12
	v_mul_f32_e32 v6, 0x42000000, v13
	v_mov_b32_e32 v17, v213
	v_cvt_pk_fp8_f32 v17, v4, v6
	v_pk_add_f32 v[6:7], v[32:33], v[108:109]
	v_pk_add_f32 v[2:3], v[34:35], v[126:127]
	v_mul_f32_e32 v4, 0x42000000, v6
	v_mul_f32_e32 v6, 0x42000000, v7
	v_mov_b32_e32 v7, v213
	v_pk_add_f32 v[10:11], v[38:39], v[122:123]
	v_mul_f32_e32 v2, 0x42000000, v2
	v_mul_f32_e32 v3, 0x42000000, v3
	v_pk_add_f32 v[12:13], v[36:37], v[104:105]
	v_cvt_pk_fp8_f32 v7, v4, v6
	v_cvt_pk_fp8_f32 v16, v2, v3 op_sel:[0,0,1]
	v_mul_f32_e32 v2, 0x42000000, v10
	v_mul_f32_e32 v3, 0x42000000, v11
	v_mul_f32_e32 v4, 0x42000000, v12
	v_mul_f32_e32 v6, 0x42000000, v13
	v_mov_b32_e32 v12, v213
	v_cvt_pk_fp8_f32 v17, v2, v3 op_sel:[0,0,1]
	v_pk_add_f32 v[2:3], v[34:35], v[110:111]
	v_cvt_pk_fp8_f32 v12, v4, v6
	v_mul_f32_e32 v2, 0x42000000, v2
	v_mul_f32_e32 v3, 0x42000000, v3
	v_pk_add_f32 v[10:11], v[38:39], v[106:107]
	v_cvt_pk_fp8_f32 v7, v2, v3 op_sel:[0,0,1]
	v_mul_f32_e32 v2, 0x42000000, v10
	v_mul_f32_e32 v3, 0x42000000, v11
	v_cvt_pk_fp8_f32 v12, v2, v3 op_sel:[0,0,1]
	s_waitcnt lgkmcnt(0)
	v_mov_b32_e32 v4, v23
	v_mov_b32_e32 v3, v22
	v_mov_b32_e32 v2, v20
	s_nop 1
	v_permlane16_swap_b32_e32 v2, v4
	v_permlane16_swap_b32_e32 v3, v5
	global_store_dwordx4 v[8:9], v[2:5], off offset:128
	v_pk_add_f32 v[8:9], v[34:35], v[94:95]
	v_pk_add_f32 v[14:15], v[36:37], v[88:89]
	v_mov_b32_e32 v4, v7
	v_mov_b32_e32 v2, v16
	v_pk_add_f32 v[10:11], v[32:33], v[92:93]
	v_mov_b32_e32 v16, v213
	v_mul_f32_e32 v7, 0x42000000, v10
	v_mul_f32_e32 v10, 0x42000000, v11
	s_waitcnt lgkmcnt(0)
	v_mov_b32_e32 v3, v17
	v_cvt_pk_fp8_f32 v16, v7, v10
	v_mul_f32_e32 v7, 0x42000000, v8
	v_mul_f32_e32 v8, 0x42000000, v9
	v_mul_f32_e32 v9, 0x42000000, v14
	v_mul_f32_e32 v10, 0x42000000, v15
	v_mov_b32_e32 v17, v213
	v_cvt_pk_fp8_f32 v17, v9, v10
	v_mov_b32_e32 v5, v12
	s_nop 1
	v_permlane16_swap_b32_e32 v2, v4
	v_permlane16_swap_b32_e32 v3, v5
	v_pk_add_f32 v[12:13], v[38:39], v[90:91]
	v_cvt_pk_fp8_f32 v16, v7, v8 op_sel:[0,0,1]
	v_mul_f32_e32 v7, 0x42000000, v12
	v_mul_f32_e32 v8, 0x42000000, v13
	v_pk_add_f32 v[10:11], v[32:33], v[84:85]
	v_cvt_pk_fp8_f32 v17, v7, v8 op_sel:[0,0,1]
	v_pk_add_f32 v[8:9], v[34:35], v[86:87]
	v_pk_add_f32 v[14:15], v[36:37], v[80:81]
	v_mul_f32_e32 v7, 0x42000000, v10
	v_mul_f32_e32 v10, 0x42000000, v11
	v_mov_b32_e32 v11, v213
	v_cvt_pk_fp8_f32 v11, v7, v10
	v_mul_f32_e32 v7, 0x42000000, v8
	v_mul_f32_e32 v8, 0x42000000, v9
	v_mul_f32_e32 v9, 0x42000000, v14
	v_mul_f32_e32 v10, 0x42000000, v15
	v_mov_b32_e32 v14, v213
	v_cvt_pk_fp8_f32 v14, v9, v10
	v_pk_add_f32 v[12:13], v[38:39], v[82:83]
	v_cvt_pk_fp8_f32 v11, v7, v8 op_sel:[0,0,1]
	v_mul_f32_e32 v7, 0x42000000, v12
	v_mul_f32_e32 v8, 0x42000000, v13
	v_cvt_pk_fp8_f32 v14, v7, v8 op_sel:[0,0,1]
	v_add_u32_e32 v18, 0x80, v18
	v_add_u32_e32 v6, v18, v201
	v_ashrrev_i32_e32 v7, 31, v6
	v_lshlrev_b64 v[6:7], 10, v[6:7]
	v_lshl_add_u64 v[6:7], s[16:17], 0, v[6:7]
	v_lshl_add_u64 v[6:7], v[6:7], 0, v[0:1]
	v_pk_add_f32 v[12:13], v[40:41], v[76:77]
	global_store_dwordx4 v[6:7], v[2:5], off
	v_mul_f32_e32 v12, 0x42000000, v12
	v_mul_f32_e32 v13, 0x42000000, v13
	s_waitcnt lgkmcnt(0)
	v_mov_b32_e32 v4, v11
	v_mov_b32_e32 v3, v17
	v_mov_b32_e32 v2, v16
	v_add_u32_e32 v8, v18, v202
	v_pk_add_f32 v[16:17], v[44:45], v[72:73]
	v_mov_b32_e32 v18, v213
	v_cvt_pk_fp8_f32 v18, v12, v13
	v_mul_f32_e32 v12, 0x42000000, v16
	v_mul_f32_e32 v13, 0x42000000, v17
	v_mov_b32_e32 v19, v213
	v_cvt_pk_fp8_f32 v19, v12, v13
	v_pk_add_f32 v[12:13], v[40:41], v[68:69]
	v_pk_add_f32 v[10:11], v[42:43], v[78:79]
	v_pk_add_f32 v[16:17], v[44:45], v[64:65]
	v_mul_f32_e32 v12, 0x42000000, v12
	v_mul_f32_e32 v13, 0x42000000, v13
	v_mov_b32_e32 v20, v213
	v_mov_b32_e32 v5, v14
	s_nop 1
	v_permlane16_swap_b32_e32 v2, v4
	v_permlane16_swap_b32_e32 v3, v5
	v_pk_add_f32 v[14:15], v[46:47], v[74:75]
	v_mul_f32_e32 v10, 0x42000000, v10
	v_mul_f32_e32 v11, 0x42000000, v11
	v_cvt_pk_fp8_f32 v20, v12, v13
	v_mul_f32_e32 v12, 0x42000000, v16
	v_mul_f32_e32 v13, 0x42000000, v17
	v_mov_b32_e32 v16, v213
	v_cvt_pk_fp8_f32 v18, v10, v11 op_sel:[0,0,1]
	v_mul_f32_e32 v10, 0x42000000, v14
	v_mul_f32_e32 v11, 0x42000000, v15
	v_cvt_pk_fp8_f32 v16, v12, v13
	v_ashrrev_i32_e32 v9, 31, v8
	v_cvt_pk_fp8_f32 v19, v10, v11 op_sel:[0,0,1]
	v_pk_add_f32 v[10:11], v[42:43], v[70:71]
	v_lshlrev_b64 v[8:9], 10, v[8:9]
	v_pk_add_f32 v[14:15], v[46:47], v[66:67]
	v_mul_f32_e32 v10, 0x42000000, v10
	v_mul_f32_e32 v11, 0x42000000, v11
	v_lshl_add_u64 v[8:9], s[16:17], 0, v[8:9]
	v_cvt_pk_fp8_f32 v20, v10, v11 op_sel:[0,0,1]
	v_mul_f32_e32 v10, 0x42000000, v14
	v_mul_f32_e32 v11, 0x42000000, v15
	v_cvt_pk_fp8_f32 v16, v10, v11 op_sel:[0,0,1]
	v_lshl_add_u64 v[8:9], v[8:9], 0, v[0:1]
	global_store_dwordx4 v[8:9], v[2:5], off
	v_pk_add_f32 v[10:11], v[44:45], v[56:57]
	v_mov_b32_e32 v14, v213
	v_pk_add_f32 v[2:3], v[40:41], v[60:61]
	v_mov_b32_e32 v15, v213
	v_mul_f32_e32 v2, 0x42000000, v2
	v_mul_f32_e32 v3, 0x42000000, v3
	v_cvt_pk_fp8_f32 v14, v2, v3
	v_mul_f32_e32 v2, 0x42000000, v10
	v_mul_f32_e32 v3, 0x42000000, v11
	v_cvt_pk_fp8_f32 v15, v2, v3
	v_pk_add_f32 v[2:3], v[40:41], v[52:53]
	v_pk_add_f32 v[0:1], v[42:43], v[62:63]
	v_pk_add_f32 v[10:11], v[44:45], v[48:49]
	v_mul_f32_e32 v2, 0x42000000, v2
	v_mul_f32_e32 v3, 0x42000000, v3
	v_mov_b32_e32 v17, v213
	v_pk_add_f32 v[4:5], v[46:47], v[58:59]
	v_mul_f32_e32 v0, 0x42000000, v0
	v_mul_f32_e32 v1, 0x42000000, v1
	v_cvt_pk_fp8_f32 v17, v2, v3
	v_mul_f32_e32 v2, 0x42000000, v10
	v_mul_f32_e32 v3, 0x42000000, v11
	v_mov_b32_e32 v10, v213
	v_cvt_pk_fp8_f32 v14, v0, v1 op_sel:[0,0,1]
	v_mul_f32_e32 v0, 0x42000000, v4
	v_mul_f32_e32 v1, 0x42000000, v5
	v_cvt_pk_fp8_f32 v10, v2, v3
	v_cvt_pk_fp8_f32 v15, v0, v1 op_sel:[0,0,1]
	v_pk_add_f32 v[0:1], v[42:43], v[54:55]
	v_pk_add_f32 v[4:5], v[46:47], v[50:51]
	v_mul_f32_e32 v0, 0x42000000, v0
	v_mul_f32_e32 v1, 0x42000000, v1
	v_cvt_pk_fp8_f32 v17, v0, v1 op_sel:[0,0,1]
	v_mul_f32_e32 v0, 0x42000000, v4
	v_mul_f32_e32 v1, 0x42000000, v5
	v_cvt_pk_fp8_f32 v10, v0, v1 op_sel:[0,0,1]
	s_waitcnt lgkmcnt(0)
	v_mov_b32_e32 v3, v16
	v_mov_b32_e32 v2, v20
	v_mov_b32_e32 v1, v19
	v_mov_b32_e32 v0, v18
	s_nop 1
	v_permlane16_swap_b32_e32 v0, v2
	v_permlane16_swap_b32_e32 v1, v3
	global_store_dwordx4 v[6:7], v[0:3], off offset:128
	s_and_b64 vcc, exec, s[6:7]
	s_mov_b64 s[6:7], -1
	s_waitcnt lgkmcnt(0)
	v_mov_b32_e32 v3, v10
	v_mov_b32_e32 v2, v17
	v_mov_b32_e32 v1, v15
	v_mov_b32_e32 v0, v14
	s_nop 1
	v_permlane16_swap_b32_e32 v0, v2
	v_permlane16_swap_b32_e32 v1, v3
	v_mov_b32_e32 v251, v230
	v_mov_b32_e32 v252, v195
	global_store_dwordx4 v[8:9], v[0:3], off offset:128
	s_cbranch_vccnz .LBB0_1050
	s_and_b64 vcc, exec, s[2:3]
	s_nop 0
	s_nop 0
	s_nop 0
	s_nop 0
	s_nop 0
	s_nop 0
	s_nop 0
	s_nop 0
	s_nop 0
	s_nop 0
	s_nop 0
	s_nop 0
	s_nop 0
	s_nop 0
	s_nop 0
	s_nop 0
	s_nop 0
	s_nop 0
	s_nop 0
	s_nop 0
	s_nop 0
	s_nop 0
	s_nop 0
	s_nop 0
	s_nop 0
	s_nop 0
	s_nop 0
	s_nop 0
	s_nop 0
	s_nop 0
	s_nop 0
	s_cbranch_vccnz .LBB0_1049
	s_barrier
	s_branch .LBB0_1049
